# QK-projection epilogue: row-statistics loads issued above the align barrier (all 6 epilogues now)
# speedup vs baseline: 1.0070x; 1.0070x over previous
; #define PG8_STAGE(bufoff, gbase, voff) do { _Pragma("unroll") for (int _i = 0; _i < 2; ++_i) \
;         __builtin_amdgcn_global_load_lds((const unsigned*)((const char*)(gbase) + (voff)[_i]), (PG8_LAS unsigned*)(lds + (bufoff) + ldsw + _i * 8192), 16, 0, 0); } while (0)
; #define PG8_LDA(dst, b, h) do { _Pragma("unroll") for (int m = 0; m < 4; ++m) _Pragma("unroll") for (int k = 0; k < 2; ++k) dst[m][k] = *(const PG8_LAS bf16x8*)(lds + PG8_SA(b, h) + aoff + m * 2048 + k * 1024); } while (0)
; #define PG8_LDB(dst, b, h) do { _Pragma("unroll") for (int n = 0; n < 2; ++n) _Pragma("unroll") for (int k = 0; k < 2; ++k) dst[n][k] = *(const PG8_LAS bf16x8*)(lds + PG8_SB(b, h) + boff + n * 2048 + k * 1024); } while (0)
; #define PG8_MMA(ai, bj, At, Bt) do { __builtin_amdgcn_s_setprio(1); _Pragma("unroll") for (int m = 0; m < 4; ++m) _Pragma("unroll") for (int n = 0; n < 2; ++n) _Pragma("unroll") for (int k = 0; k < 2; ++k) \
;         acc[ai][bj][m][n] = __builtin_amdgcn_mfma_f32_16x16x32_bf16(Bt[n][k], At[m][k], acc[ai][bj][m][n], 0, 0, 0); __builtin_amdgcn_s_setprio(0); } while (0)
; #define PG8_WAIT_V(n) asm volatile("s_waitcnt vmcnt(" #n ")" ::: "memory")
; #define PG8_WAIT_L(n) asm volatile("s_waitcnt lgkmcnt(" #n ")" ::: "memory")
; template <class Epi, class Sched, bool ALIGN_EPI = false, bool SP2 = false>
; __device__ __forceinline__ void gemm_phase(PG8_LAS unsigned char* lds, const Gemm g, const Sched& S, const Epi& E) {
;     ...
;             const bool last = (t == nt - 2);
;             const char* a1 = cA + (size_t)(t + 1) * kstep;
;             const char* a2 = last ? nA : cA + (size_t)(t + 2) * kstep; const char* b2 = last ? nB : cB + (size_t)(t + 2) * kstep;
;             const char* a3 = a2 + kstep; const char* b3 = b2 + kstep;
;             if (last && has_next) S.a_ready(nxt);
;             if constexpr (SP2) {
;             PG8_LDB(B0, 0, 0); PG8_LDB(B1, 0, 1); PG8_SCHED; PG8_LDA(At, 0, 0); PG8_STAGE(PG8_SA(1, 1), a1 + hstep, voffA);
;             PG8_WAIT_V(8); PG8_WAIT_L(0); PG8_BAR; PG8_MMA(0, 0, At, B0); PG8_MMA(0, 1, At, B1); PG8_BAR; PG8_SCHED;
;             PG8_LDA(At, 0, 1); PG8_STAGE(PG8_SB(0, 0), b2, voffB); PG8_STAGE(PG8_SB(0, 1), b2 + hstep, voffB); PG8_STAGE(PG8_SA(0, 0), a2, voffA);
;             PG8_WAIT_V(8); PG8_WAIT_L(0); PG8_BAR; PG8_MMA(1, 0, At, B0); PG8_MMA(1, 1, At, B1); PG8_BAR; PG8_SCHED;
.LBB0_242:
	s_add_u32 s36, s18, 0xfffc0080
	s_addc_u32 s37, s19, -1
	s_add_i32 s52, 0, 0x10000
	s_cmp_eq_u32 s51, 12
	s_cselect_b32 s63, s1, s37
	s_cselect_b32 s62, s30, s36
	s_cselect_b32 s37, s31, s49
	s_cselect_b32 s36, s34, s35
	s_add_i32 s67, 0, 0x14000
	v_add_u32_e32 v110, s52, v180
	v_add_u32_e32 v170, s67, v180
	ds_read_b128 v[98:101], v110
	ds_read_b128 v[102:105], v110 offset:1024
	ds_read_b128 v[106:109], v110 offset:2048
	ds_read_b128 v[110:113], v110 offset:3072
	ds_read_b128 v[158:161], v170
	ds_read_b128 v[162:165], v170 offset:1024
	ds_read_b128 v[166:169], v170 offset:2048
	ds_read_b128 v[170:173], v170 offset:3072
	v_lshl_add_u64 v[174:175], s[18:19], 0, v[154:155]
	s_add_i32 m0, s27, 0xc000
	ds_read_b128 v[184:187], v182
	ds_read_b128 v[194:197], v182 offset:1024
	ds_read_b128 v[198:201], v182 offset:2048
	ds_read_b128 v[202:205], v182 offset:3072
	ds_read_b128 v[206:209], v182 offset:4096
	ds_read_b128 v[210:213], v182 offset:5120
	ds_read_b128 v[214:217], v182 offset:6144
	ds_read_b128 v[218:221], v182 offset:7168
	global_load_lds_dwordx4 v[174:175], off
	v_lshl_add_u64 v[174:175], s[18:19], 0, v[156:157]
	s_add_i32 m0, s27, 0xe000
	s_nop 0
	global_load_lds_dwordx4 v[174:175], off
	s_waitcnt vmcnt(8)
	s_waitcnt lgkmcnt(0)
	s_barrier
	s_setprio 1
	s_waitcnt lgkmcnt(0)
	v_mfma_f32_16x16x32_bf16 v[142:145], v[98:101], v[184:187], v[142:145]
	v_mfma_f32_16x16x32_bf16 v[138:141], v[106:109], v[184:187], v[138:141]
	v_mfma_f32_16x16x32_bf16 v[126:129], v[98:101], v[198:201], v[126:129]
	v_mfma_f32_16x16x32_bf16 v[122:125], v[106:109], v[198:201], v[122:125]
	v_mfma_f32_16x16x32_bf16 v[94:97], v[98:101], v[206:209], v[94:97]
	v_mfma_f32_16x16x32_bf16 v[90:93], v[106:109], v[206:209], v[90:93]
	v_mfma_f32_16x16x32_bf16 v[78:81], v[98:101], v[214:217], v[78:81]
	v_mfma_f32_16x16x32_bf16 v[74:77], v[106:109], v[214:217], v[74:77]
	v_mfma_f32_16x16x32_bf16 v[142:145], v[102:105], v[194:197], v[142:145]
	v_mfma_f32_16x16x32_bf16 v[138:141], v[110:113], v[194:197], v[138:141]
	v_mfma_f32_16x16x32_bf16 v[126:129], v[102:105], v[202:205], v[126:129]
	v_mfma_f32_16x16x32_bf16 v[122:125], v[110:113], v[202:205], v[122:125]
	v_mfma_f32_16x16x32_bf16 v[94:97], v[102:105], v[210:213], v[94:97]
	v_mfma_f32_16x16x32_bf16 v[90:93], v[110:113], v[210:213], v[90:93]
	v_mfma_f32_16x16x32_bf16 v[78:81], v[102:105], v[218:221], v[78:81]
	v_mfma_f32_16x16x32_bf16 v[74:77], v[110:113], v[218:221], v[74:77]
	s_setprio 0
	s_setprio 1
	v_mfma_f32_16x16x32_bf16 v[134:137], v[158:161], v[184:187], v[134:137]
	v_mfma_f32_16x16x32_bf16 v[130:133], v[166:169], v[184:187], v[130:133]
	v_mfma_f32_16x16x32_bf16 v[118:121], v[158:161], v[198:201], v[118:121]
	v_mfma_f32_16x16x32_bf16 v[114:117], v[166:169], v[198:201], v[114:117]
	v_mfma_f32_16x16x32_bf16 v[86:89], v[158:161], v[206:209], v[86:89]
	v_mfma_f32_16x16x32_bf16 v[82:85], v[166:169], v[206:209], v[82:85]
	v_mfma_f32_16x16x32_bf16 v[70:73], v[158:161], v[214:217], v[70:73]
	v_mfma_f32_16x16x32_bf16 v[66:69], v[166:169], v[214:217], v[66:69]
	v_mfma_f32_16x16x32_bf16 v[134:137], v[162:165], v[194:197], v[134:137]
	v_mfma_f32_16x16x32_bf16 v[130:133], v[170:173], v[194:197], v[130:133]
	v_mfma_f32_16x16x32_bf16 v[118:121], v[162:165], v[202:205], v[118:121]
	v_mfma_f32_16x16x32_bf16 v[114:117], v[170:173], v[202:205], v[114:117]
	v_mfma_f32_16x16x32_bf16 v[86:89], v[162:165], v[210:213], v[86:89]
	v_mfma_f32_16x16x32_bf16 v[82:85], v[170:173], v[210:213], v[82:85]
	v_mfma_f32_16x16x32_bf16 v[70:73], v[162:165], v[218:221], v[70:73]
	v_mfma_f32_16x16x32_bf16 v[66:69], v[170:173], v[218:221], v[66:69]
	s_setprio 0
	s_barrier
	s_add_i32 s52, s52, s24
	v_lshl_add_u64 v[174:175], s[36:37], 0, v[0:1]
	s_mov_b32 m0, s52
	ds_read_b128 v[184:187], v182 offset:16384
	ds_read_b128 v[194:197], v182 offset:17408
	ds_read_b128 v[198:201], v182 offset:18432
	ds_read_b128 v[202:205], v182 offset:19456
	ds_read_b128 v[206:209], v182 offset:20480
	ds_read_b128 v[210:213], v182 offset:21504
	ds_read_b128 v[214:217], v182 offset:22528
	ds_read_b128 v[218:221], v182 offset:23552
	global_load_lds_dwordx4 v[174:175], off
	s_add_i32 m0, s52, 0x2000
	s_add_u32 s52, s36, 0x40000
	v_lshl_add_u64 v[178:179], s[36:37], 0, v[150:151]
	s_addc_u32 s53, s37, 0
	s_add_i32 s67, s67, s24
	global_load_lds_dwordx4 v[178:179], off
	v_lshl_add_u64 v[188:189], s[52:53], 0, v[0:1]
	s_mov_b32 m0, s67
	v_lshl_add_u64 v[222:223], s[62:63], 0, v[148:149]
	global_load_lds_dwordx4 v[188:189], off
	v_lshl_add_u64 v[188:189], s[52:53], 0, v[150:151]
	s_add_i32 m0, s67, 0x2000
	s_nop 0
	global_load_lds_dwordx4 v[188:189], off
	v_lshl_add_u64 v[188:189], s[62:63], 0, v[146:147]
	s_mov_b32 m0, s27
	s_nop 0
	global_load_lds_dwordx4 v[188:189], off
	s_mov_b32 m0, s28
	s_nop 0
	global_load_lds_dwordx4 v[222:223], off
	s_waitcnt vmcnt(8)
	s_waitcnt lgkmcnt(0)
	s_barrier
; #define PG8_STAGE(bufoff, gbase, voff) do { _Pragma("unroll") for (int _i = 0; _i < 2; ++_i) \
;         __builtin_amdgcn_global_load_lds((const unsigned*)((const char*)(gbase) + (voff)[_i]), (PG8_LAS unsigned*)(lds + (bufoff) + ldsw + _i * 8192), 16, 0, 0); } while (0)
; #define PG8_LDA(dst, b, h) do { _Pragma("unroll") for (int m = 0; m < 4; ++m) _Pragma("unroll") for (int k = 0; k < 2; ++k) dst[m][k] = *(const PG8_LAS bf16x8*)(lds + PG8_SA(b, h) + aoff + m * 2048 + k * 1024); } while (0)
; #define PG8_LDB(dst, b, h) do { _Pragma("unroll") for (int n = 0; n < 2; ++n) _Pragma("unroll") for (int k = 0; k < 2; ++k) dst[n][k] = *(const PG8_LAS bf16x8*)(lds + PG8_SB(b, h) + boff + n * 2048 + k * 1024); } while (0)
; #define PG8_MMA(ai, bj, At, Bt) do { __builtin_amdgcn_s_setprio(1); _Pragma("unroll") for (int m = 0; m < 4; ++m) _Pragma("unroll") for (int n = 0; n < 2; ++n) _Pragma("unroll") for (int k = 0; k < 2; ++k) \
;         acc[ai][bj][m][n] = __builtin_amdgcn_mfma_f32_16x16x32_bf16(Bt[n][k], At[m][k], acc[ai][bj][m][n], 0, 0, 0); __builtin_amdgcn_s_setprio(0); } while (0)
; #define PG8_WAIT_V(n) asm volatile("s_waitcnt vmcnt(" #n ")" ::: "memory")
; #define PG8_WAIT_L(n) asm volatile("s_waitcnt lgkmcnt(" #n ")" ::: "memory")
; #define PG8_BAR __builtin_amdgcn_s_barrier()
; #define PG8_SCHED __builtin_amdgcn_sched_barrier(0)
; template <class Epi, class Sched, bool ALIGN_EPI = false, bool SP2 = false>
; __device__ __forceinline__ void gemm_phase(PG8_LAS unsigned char* lds, const Gemm g, const Sched& S, const Epi& E) {
;     ...
;             PG8_WAIT_V(8); PG8_WAIT_L(0); PG8_BAR; PG8_MMA(1, 0, At, B0); PG8_MMA(1, 1, At, B1); PG8_BAR; PG8_SCHED;
;             PG8_LDB(B0, 1, 0); PG8_LDB(B1, 1, 1); PG8_SCHED; PG8_LDA(At, 1, 0); PG8_STAGE(PG8_SA(0, 1), a2 + hstep, voffA);
;             PG8_WAIT_V(8); PG8_WAIT_L(0); PG8_BAR; PG8_MMA(0, 0, At, B0); PG8_MMA(0, 1, At, B1); PG8_BAR; PG8_SCHED;
	s_setprio 1
	s_waitcnt lgkmcnt(0)
	v_mfma_f32_16x16x32_bf16 v[62:65], v[98:101], v[184:187], v[62:65]
	v_mfma_f32_16x16x32_bf16 v[58:61], v[106:109], v[184:187], v[58:61]
	v_mfma_f32_16x16x32_bf16 v[46:49], v[98:101], v[198:201], v[46:49]
	v_mfma_f32_16x16x32_bf16 v[42:45], v[106:109], v[198:201], v[42:45]
	v_mfma_f32_16x16x32_bf16 v[30:33], v[98:101], v[206:209], v[30:33]
	v_mfma_f32_16x16x32_bf16 v[26:29], v[106:109], v[206:209], v[26:29]
	v_mfma_f32_16x16x32_bf16 v[14:17], v[98:101], v[214:217], v[14:17]
	v_mfma_f32_16x16x32_bf16 v[10:13], v[106:109], v[214:217], v[10:13]
	v_mfma_f32_16x16x32_bf16 v[62:65], v[102:105], v[194:197], v[62:65]
	v_mfma_f32_16x16x32_bf16 v[58:61], v[110:113], v[194:197], v[58:61]
	v_mfma_f32_16x16x32_bf16 v[46:49], v[102:105], v[202:205], v[46:49]
	v_mfma_f32_16x16x32_bf16 v[42:45], v[110:113], v[202:205], v[42:45]
	v_mfma_f32_16x16x32_bf16 v[30:33], v[102:105], v[210:213], v[30:33]
	v_mfma_f32_16x16x32_bf16 v[26:29], v[110:113], v[210:213], v[26:29]
	v_mfma_f32_16x16x32_bf16 v[14:17], v[102:105], v[218:221], v[14:17]
	v_mfma_f32_16x16x32_bf16 v[10:13], v[110:113], v[218:221], v[10:13]
	s_setprio 0
	s_setprio 1
	v_mfma_f32_16x16x32_bf16 v[54:57], v[158:161], v[184:187], v[54:57]
	v_mfma_f32_16x16x32_bf16 v[50:53], v[166:169], v[184:187], v[50:53]
	v_mfma_f32_16x16x32_bf16 v[38:41], v[158:161], v[198:201], v[38:41]
	v_mfma_f32_16x16x32_bf16 v[34:37], v[166:169], v[198:201], v[34:37]
	v_mfma_f32_16x16x32_bf16 v[22:25], v[158:161], v[206:209], v[22:25]
	v_mfma_f32_16x16x32_bf16 v[18:21], v[166:169], v[206:209], v[18:21]
	v_mfma_f32_16x16x32_bf16 v[6:9], v[158:161], v[214:217], v[6:9]
	v_mfma_f32_16x16x32_bf16 v[2:5], v[166:169], v[214:217], v[2:5]
	v_mfma_f32_16x16x32_bf16 v[54:57], v[162:165], v[194:197], v[54:57]
	v_mfma_f32_16x16x32_bf16 v[50:53], v[170:173], v[194:197], v[50:53]
	v_mfma_f32_16x16x32_bf16 v[38:41], v[162:165], v[202:205], v[38:41]
	v_mfma_f32_16x16x32_bf16 v[34:37], v[170:173], v[202:205], v[34:37]
	v_mfma_f32_16x16x32_bf16 v[22:25], v[162:165], v[210:213], v[22:25]
	v_mfma_f32_16x16x32_bf16 v[18:21], v[170:173], v[210:213], v[18:21]
	v_mfma_f32_16x16x32_bf16 v[6:9], v[162:165], v[218:221], v[6:9]
	v_mfma_f32_16x16x32_bf16 v[2:5], v[170:173], v[218:221], v[2:5]
	s_setprio 0
	s_barrier
	s_add_i32 s67, 0, 0x18000
	s_add_i32 s68, 0, 0x1c000
	v_add_u32_e32 v110, s67, v180
	v_add_u32_e32 v170, s68, v180
	ds_read_b128 v[98:101], v110
	ds_read_b128 v[102:105], v110 offset:1024
	ds_read_b128 v[106:109], v110 offset:2048
	ds_read_b128 v[110:113], v110 offset:3072
	ds_read_b128 v[158:161], v170
	ds_read_b128 v[162:165], v170 offset:1024
	ds_read_b128 v[166:169], v170 offset:2048
	ds_read_b128 v[170:173], v170 offset:3072
	s_add_u32 s52, s62, 0x40000
	s_addc_u32 s53, s63, 0
	s_mov_b32 m0, s29
	v_lshl_add_u64 v[224:225], s[52:53], 0, v[146:147]
	ds_read_b128 v[184:187], v182 offset:32768
	ds_read_b128 v[194:197], v182 offset:33792
	ds_read_b128 v[198:201], v182 offset:34816
	ds_read_b128 v[202:205], v182 offset:35840
	ds_read_b128 v[206:209], v182 offset:36864
	ds_read_b128 v[210:213], v182 offset:37888
	ds_read_b128 v[214:217], v182 offset:38912
	ds_read_b128 v[218:221], v182 offset:39936
	global_load_lds_dwordx4 v[224:225], off
	v_lshl_add_u64 v[224:225], s[52:53], 0, v[148:149]
	s_mov_b32 m0, s61
	s_nop 0
	global_load_lds_dwordx4 v[224:225], off
	s_waitcnt vmcnt(8)
	s_waitcnt lgkmcnt(0)
	s_barrier
	s_setprio 1
	s_waitcnt lgkmcnt(0)
	v_mfma_f32_16x16x32_bf16 v[142:145], v[98:101], v[184:187], v[142:145]
	v_mfma_f32_16x16x32_bf16 v[138:141], v[106:109], v[184:187], v[138:141]
	v_mfma_f32_16x16x32_bf16 v[126:129], v[98:101], v[198:201], v[126:129]
	v_mfma_f32_16x16x32_bf16 v[122:125], v[106:109], v[198:201], v[122:125]
	v_mfma_f32_16x16x32_bf16 v[94:97], v[98:101], v[206:209], v[94:97]
	v_mfma_f32_16x16x32_bf16 v[90:93], v[106:109], v[206:209], v[90:93]
	v_mfma_f32_16x16x32_bf16 v[78:81], v[98:101], v[214:217], v[78:81]
	v_mfma_f32_16x16x32_bf16 v[74:77], v[106:109], v[214:217], v[74:77]
	v_mfma_f32_16x16x32_bf16 v[142:145], v[102:105], v[194:197], v[142:145]
	v_mfma_f32_16x16x32_bf16 v[138:141], v[110:113], v[194:197], v[138:141]
	v_mfma_f32_16x16x32_bf16 v[126:129], v[102:105], v[202:205], v[126:129]
	v_mfma_f32_16x16x32_bf16 v[122:125], v[110:113], v[202:205], v[122:125]
	v_mfma_f32_16x16x32_bf16 v[94:97], v[102:105], v[210:213], v[94:97]
	v_mfma_f32_16x16x32_bf16 v[90:93], v[110:113], v[210:213], v[90:93]
	v_mfma_f32_16x16x32_bf16 v[78:81], v[102:105], v[218:221], v[78:81]
	v_mfma_f32_16x16x32_bf16 v[74:77], v[110:113], v[218:221], v[74:77]
	s_setprio 0
	s_setprio 1
	v_mfma_f32_16x16x32_bf16 v[134:137], v[158:161], v[184:187], v[134:137]
	v_mfma_f32_16x16x32_bf16 v[130:133], v[166:169], v[184:187], v[130:133]
	v_mfma_f32_16x16x32_bf16 v[118:121], v[158:161], v[198:201], v[118:121]
	v_mfma_f32_16x16x32_bf16 v[114:117], v[166:169], v[198:201], v[114:117]
	v_mfma_f32_16x16x32_bf16 v[86:89], v[158:161], v[206:209], v[86:89]
	v_mfma_f32_16x16x32_bf16 v[82:85], v[166:169], v[206:209], v[82:85]
	v_mfma_f32_16x16x32_bf16 v[70:73], v[158:161], v[214:217], v[70:73]
	v_mfma_f32_16x16x32_bf16 v[66:69], v[166:169], v[214:217], v[66:69]
	v_mfma_f32_16x16x32_bf16 v[134:137], v[162:165], v[194:197], v[134:137]
	v_mfma_f32_16x16x32_bf16 v[130:133], v[170:173], v[194:197], v[130:133]
	v_mfma_f32_16x16x32_bf16 v[118:121], v[162:165], v[202:205], v[118:121]
	v_mfma_f32_16x16x32_bf16 v[114:117], v[170:173], v[202:205], v[114:117]
	v_mfma_f32_16x16x32_bf16 v[86:89], v[162:165], v[210:213], v[86:89]
	v_mfma_f32_16x16x32_bf16 v[82:85], v[170:173], v[210:213], v[82:85]
	v_mfma_f32_16x16x32_bf16 v[70:73], v[162:165], v[218:221], v[70:73]
	v_mfma_f32_16x16x32_bf16 v[66:69], v[170:173], v[218:221], v[66:69]
	s_setprio 0
	s_barrier
; #define PG8_STAGE(bufoff, gbase, voff) do { _Pragma("unroll") for (int _i = 0; _i < 2; ++_i) \
;         __builtin_amdgcn_global_load_lds((const unsigned*)((const char*)(gbase) + (voff)[_i]), (PG8_LAS unsigned*)(lds + (bufoff) + ldsw + _i * 8192), 16, 0, 0); } while (0)
; #define PG8_LDA(dst, b, h) do { _Pragma("unroll") for (int m = 0; m < 4; ++m) _Pragma("unroll") for (int k = 0; k < 2; ++k) dst[m][k] = *(const PG8_LAS bf16x8*)(lds + PG8_SA(b, h) + aoff + m * 2048 + k * 1024); } while (0)
; #define PG8_MMA(ai, bj, At, Bt) do { __builtin_amdgcn_s_setprio(1); _Pragma("unroll") for (int m = 0; m < 4; ++m) _Pragma("unroll") for (int n = 0; n < 2; ++n) _Pragma("unroll") for (int k = 0; k < 2; ++k) \
;         acc[ai][bj][m][n] = __builtin_amdgcn_mfma_f32_16x16x32_bf16(Bt[n][k], At[m][k], acc[ai][bj][m][n], 0, 0, 0); __builtin_amdgcn_s_setprio(0); } while (0)
; #define PG8_WAIT_V(n) asm volatile("s_waitcnt vmcnt(" #n ")" ::: "memory")
; #define PG8_WAIT_L(n) asm volatile("s_waitcnt lgkmcnt(" #n ")" ::: "memory")
; #define PG8_BAR __builtin_amdgcn_s_barrier()
; #define PG8_SCHED __builtin_amdgcn_sched_barrier(0)
; template <class Epi, class Sched, bool ALIGN_EPI = false, bool SP2 = false>
; __device__ __forceinline__ void gemm_phase(PG8_LAS unsigned char* lds, const Gemm g, const Sched& S, const Epi& E) {
;     ...
;             PG8_WAIT_V(8); PG8_WAIT_L(0); PG8_BAR; PG8_MMA(0, 0, At, B0); PG8_MMA(0, 1, At, B1); PG8_BAR; PG8_SCHED;
;             PG8_LDA(At, 1, 1); PG8_STAGE(PG8_SB(1, 0), b3, voffB); PG8_STAGE(PG8_SB(1, 1), b3 + hstep, voffB); PG8_STAGE(PG8_SA(1, 0), a3, voffA);
;             PG8_WAIT_V(8); PG8_WAIT_L(0); PG8_BAR; PG8_MMA(1, 0, At, B0); PG8_MMA(1, 1, At, B1); PG8_BAR; PG8_SCHED;
;     ...
;         if constexpr (ALIGN_EPI) { if (wr == 0) PG8_BAR; }
	s_add_i32 s52, s67, s24
	v_lshl_add_u64 v[174:175], v[174:175], 0, s[8:9]
	s_mov_b32 m0, s52
	ds_read_b128 v[184:187], v182 offset:49152
	ds_read_b128 v[194:197], v182 offset:50176
	ds_read_b128 v[198:201], v182 offset:51200
	ds_read_b128 v[202:205], v182 offset:52224
	ds_read_b128 v[206:209], v182 offset:53248
	ds_read_b128 v[210:213], v182 offset:54272
	ds_read_b128 v[214:217], v182 offset:55296
	ds_read_b128 v[218:221], v182 offset:56320
	global_load_lds_dwordx4 v[174:175], off
	s_add_i32 m0, s52, 0x2000
	s_add_u32 s36, s36, 0x40080
	v_lshl_add_u64 v[174:175], v[178:179], 0, s[8:9]
	s_addc_u32 s37, s37, 0
	s_add_i32 s52, s68, s24
	global_load_lds_dwordx4 v[174:175], off
	v_lshl_add_u64 v[174:175], s[36:37], 0, v[0:1]
	s_mov_b32 m0, s52
	s_nop 0
	global_load_lds_dwordx4 v[174:175], off
	v_lshl_add_u64 v[174:175], s[36:37], 0, v[150:151]
	s_add_i32 m0, s52, 0x2000
	s_nop 0
	global_load_lds_dwordx4 v[174:175], off
	v_lshl_add_u64 v[174:175], v[188:189], 0, s[8:9]
	s_mov_b32 m0, s64
	s_nop 0
	global_load_lds_dwordx4 v[174:175], off
	v_lshl_add_u64 v[174:175], v[222:223], 0, s[8:9]
	s_mov_b32 m0, s65
	s_nop 0
	global_load_lds_dwordx4 v[174:175], off
	s_waitcnt vmcnt(8)
	s_waitcnt lgkmcnt(0)
	s_barrier
	s_setprio 1
	s_waitcnt lgkmcnt(0)
	v_mfma_f32_16x16x32_bf16 v[62:65], v[98:101], v[184:187], v[62:65]
	v_mfma_f32_16x16x32_bf16 v[58:61], v[106:109], v[184:187], v[58:61]
	v_mfma_f32_16x16x32_bf16 v[46:49], v[98:101], v[198:201], v[46:49]
	v_mfma_f32_16x16x32_bf16 v[42:45], v[106:109], v[198:201], v[42:45]
	v_mfma_f32_16x16x32_bf16 v[30:33], v[98:101], v[206:209], v[30:33]
	v_mfma_f32_16x16x32_bf16 v[26:29], v[106:109], v[206:209], v[26:29]
	v_mfma_f32_16x16x32_bf16 v[14:17], v[98:101], v[214:217], v[14:17]
	v_mfma_f32_16x16x32_bf16 v[10:13], v[106:109], v[214:217], v[10:13]
	v_mfma_f32_16x16x32_bf16 v[62:65], v[102:105], v[194:197], v[62:65]
	v_mfma_f32_16x16x32_bf16 v[58:61], v[110:113], v[194:197], v[58:61]
	v_mfma_f32_16x16x32_bf16 v[46:49], v[102:105], v[202:205], v[46:49]
	v_mfma_f32_16x16x32_bf16 v[42:45], v[110:113], v[202:205], v[42:45]
	v_mfma_f32_16x16x32_bf16 v[30:33], v[102:105], v[210:213], v[30:33]
	v_mfma_f32_16x16x32_bf16 v[26:29], v[110:113], v[210:213], v[26:29]
	v_mfma_f32_16x16x32_bf16 v[14:17], v[102:105], v[218:221], v[14:17]
	v_mfma_f32_16x16x32_bf16 v[10:13], v[110:113], v[218:221], v[10:13]
	s_setprio 0
	s_setprio 1
	v_mfma_f32_16x16x32_bf16 v[54:57], v[158:161], v[184:187], v[54:57]
	v_mfma_f32_16x16x32_bf16 v[50:53], v[166:169], v[184:187], v[50:53]
	v_mfma_f32_16x16x32_bf16 v[38:41], v[158:161], v[198:201], v[38:41]
	v_mfma_f32_16x16x32_bf16 v[34:37], v[166:169], v[198:201], v[34:37]
	v_mfma_f32_16x16x32_bf16 v[22:25], v[158:161], v[206:209], v[22:25]
	v_mfma_f32_16x16x32_bf16 v[18:21], v[166:169], v[206:209], v[18:21]
	v_mfma_f32_16x16x32_bf16 v[6:9], v[158:161], v[214:217], v[6:9]
	v_mfma_f32_16x16x32_bf16 v[2:5], v[166:169], v[214:217], v[2:5]
	v_mfma_f32_16x16x32_bf16 v[54:57], v[162:165], v[194:197], v[54:57]
	v_mfma_f32_16x16x32_bf16 v[50:53], v[170:173], v[194:197], v[50:53]
	v_mfma_f32_16x16x32_bf16 v[38:41], v[162:165], v[202:205], v[38:41]
	v_mfma_f32_16x16x32_bf16 v[34:37], v[170:173], v[202:205], v[34:37]
	v_mfma_f32_16x16x32_bf16 v[22:25], v[162:165], v[210:213], v[22:25]
	v_mfma_f32_16x16x32_bf16 v[18:21], v[170:173], v[210:213], v[18:21]
	v_mfma_f32_16x16x32_bf16 v[6:9], v[162:165], v[218:221], v[6:9]
	v_mfma_f32_16x16x32_bf16 v[2:5], v[170:173], v[218:221], v[2:5]
	s_setprio 0
	s_barrier
	s_add_i32 s51, s51, 2
	s_add_u32 s18, s18, 0x100
	s_addc_u32 s19, s19, 0
	s_add_u32 s35, s35, 0x100
	s_addc_u32 s49, s49, 0
	s_cmp_gt_u32 s51, 13
	s_cbranch_scc0 .LBB0_242


; #define PG8_BAR __builtin_amdgcn_s_barrier()
; template <class Epi, class Sched, bool ALIGN_EPI = false, bool SP2 = false>
; __device__ __forceinline__ void gemm_phase(PG8_LAS unsigned char* lds, const Gemm g, const Sched& S, const Epi& E) {
;     ...
;         if constexpr (ALIGN_EPI) { if (wr == 0) PG8_BAR; }
;     __device__ __forceinline__ void operator()(const f32x4 (&acc)[2][2][4][2], const pg8::Unit& u, int wr, int wc, int fr, int fq) const {
;         const int pn = u.pn, row0 = u.pm * 256 + wr * 64 + fr, col0 = pn * 256 + wc * 64 + 8 * fq;
;         const float* g = gains + (pn < 2 ? 0 : (pn < 4 ? 64 : (pn == 4 ? 128 : (pn == 5 ? 160 : 192))));
;         const int gstep = pn < 4 ? 32 : 0;
;         const float osc = (pn < 2 || pn == 6) ? 0.125f * LOG2E : (pn == 4 ? 0.17677669529663687f * LOG2E : 1.0f);
;         const float inv_n = pn < 4 ? (1.0f / 64.0f) : (1.0f / 32.0f);
;         const float* gp = g + 8 * fq;
;         u64 sv[2][4];
; #pragma unroll
;         for (int ai = 0; ai < 2; ++ai)
; #pragma unroll
;             for (int m = 0; m < 4; ++m) sv[ai][m] = ss[row0 + ai * 128 + m * 16];
;         f32x4 gg[2][2];
; #pragma unroll
;         for (int bj = 0; bj < 2; ++bj) { gg[bj][0] = *(const f32x4*)(gp + bj * gstep); gg[bj][1] = *(const f32x4*)(gp + bj * gstep + 4); }
; #pragma unroll
;         for (int ai = 0; ai < 2; ++ai)
; #pragma unroll
;             for (int m = 0; m < 4; ++m) {
;                 const int row = row0 + ai * 128 + m * 16;
;                 const float r = __builtin_amdgcn_rsqf((float)sv[ai][m] * SS_INV + 1e-6f);
;                 float s0, s1;
;                 { const f32x4 a = acc[ai][0][m][0] * r, b = acc[ai][0][m][1] * r; s0 = (a[0] * a[0] + a[1] * a[1]) + (a[2] * a[2] + a[3] * a[3]) + (b[0] * b[0] + b[1] * b[1]) + (b[2] * b[2] + b[3] * b[3]); }
;                 { const f32x4 a = acc[ai][1][m][0] * r, b = acc[ai][1][m][1] * r; s1 = (a[0] * a[0] + a[1] * a[1]) + (a[2] * a[2] + a[3] * a[3]) + (b[0] * b[0] + b[1] * b[1]) + (b[2] * b[2] + b[3] * b[3]); }
;                 if (pn < 4) { s0 += s1; s1 = s0; }
;                 s0 += __shfl_xor(s0, 16); s1 += __shfl_xor(s1, 16); s0 += __shfl_xor(s0, 32); s1 += __shfl_xor(s1, 32);
.LBB0_245:
	v_lshl_add_u32 v160, s0, 8, v177
	v_ashrrev_i32_e32 v161, 31, v160
	v_lshl_add_u64 v[98:99], v[160:161], 3, s[40:41]
	global_load_dwordx2 v[164:165], v[98:99], off
	global_load_dwordx2 v[174:175], v[98:99], off offset:128
	global_load_dwordx2 v[172:173], v[98:99], off offset:256
	global_load_dwordx2 v[170:171], v[98:99], off offset:384
	global_load_dwordx2 v[168:169], v[98:99], off offset:1024
	global_load_dwordx2 v[166:167], v[98:99], off offset:1152
	global_load_dwordx2 v[162:163], v[98:99], off offset:1280
	global_load_dwordx2 v[158:159], v[98:99], off offset:1408
	s_and_b64 vcc, exec, s[46:47]
	s_cbranch_vccz .Lalign_go_0
	s_barrier
.Lalign_go_0:
	s_cmp_eq_u32 s60, 5
	s_movk_i32 s0, 0xa0
	s_cselect_b32 s18, s0, 0xc0
	s_cmp_eq_u32 s60, 4
	s_cselect_b64 vcc, -1, 0
	s_and_b64 s[0:1], vcc, exec
	s_cselect_b32 s0, 0x80, s18
	s_cmp_gt_u32 s60, 3
	s_cselect_b32 s18, s0, 64
	s_cmp_eq_u32 s60, 6
	s_cselect_b64 s[0:1], -1, 0
	s_cmp_lt_i32 s60, 2
	s_cselect_b64 s[30:31], -1, 0
	s_and_b64 s[34:35], s[30:31], exec
	v_cndmask_b32_e32 v202, 1.0, v232, vcc
	s_cselect_b32 s18, 0, s18
	s_or_b64 vcc, s[30:31], s[0:1]
	s_cmp_lt_i32 s60, 4
	s_cselect_b64 s[0:1], -1, 0
	s_and_b64 s[30:31], s[0:1], exec
	s_mov_b32 s19, s93
	s_cselect_b32 s92, 0x80, 0
	s_lshl_b32 s18, s18, 2
	v_lshl_add_u64 v[98:99], v[152:153], 0, s[18:19]
	v_lshl_add_u64 v[102:103], v[98:99], 0, s[92:93]
	global_load_dwordx4 v[106:109], v[98:99], off offset:16
	global_load_dwordx4 v[110:113], v[98:99], off
	s_nop 0
	global_load_dwordx4 v[98:101], v[102:103], off offset:16
	s_nop 0
	global_load_dwordx4 v[102:105], v[102:103], off
	v_and_b32_e32 v178, 64, v236
	v_xor_b32_e32 v176, 16, v236
	v_add_u32_e32 v178, 64, v178
	v_cmp_lt_i32_e64 s[36:37], v176, v178
	v_xor_b32_e32 v179, 32, v236
	s_cmp_lt_i32 s60, 6
	v_cndmask_b32_e64 v183, v234, v235, s[0:1]
	s_cselect_b64 s[18:19], -1, 0
	s_cmp_gt_i32 s60, 5
	s_waitcnt vmcnt(0)
	v_ffbh_u32_e32 v184, v165
	v_min_u32_e32 v184, 32, v184
	v_lshlrev_b64 v[164:165], v184, v[164:165]
	v_min_u32_e32 v164, 1, v164
	v_or_b32_e32 v164, v165, v164
	v_cvt_f32_u32_e32 v164, v164
	v_cndmask_b32_e64 v165, v236, v176, s[36:37]
	v_sub_u32_e32 v176, 32, v184
	v_cmp_lt_i32_e64 s[36:37], v179, v178
	v_ldexp_f32 v164, v164, v176
	v_fmamk_f32 v164, v164, 0x30800000, v229
	v_rsq_f32_e32 v176, v164
	v_cndmask_b32_e64 v185, v236, v179, s[36:37]
	v_lshlrev_b32_e32 v184, 2, v165
	v_lshlrev_b32_e32 v185, 2, v185
	v_pk_mul_f32 v[164:165], v[144:145], v[176:177] op_sel_hi:[1,0]
	v_pk_mul_f32 v[178:179], v[142:143], v[176:177] op_sel_hi:[1,0]
	v_pk_mul_f32 v[194:195], v[136:137], v[176:177] op_sel_hi:[1,0]
	v_pk_mul_f32 v[196:197], v[134:135], v[176:177] op_sel_hi:[1,0]
	v_pk_mul_f32 v[188:189], v[138:139], v[176:177] op_sel_hi:[1,0]
	v_pk_mul_f32 v[200:201], v[130:131], v[176:177] op_sel_hi:[1,0]
	v_mul_f32_e32 v179, v179, v179
	v_mul_f32_e32 v165, v165, v165
	v_mul_f32_e32 v197, v197, v197
	v_mul_f32_e32 v195, v195, v195
	v_pk_mul_f32 v[186:187], v[140:141], v[176:177] op_sel_hi:[1,0]
	v_pk_mul_f32 v[198:199], v[132:133], v[176:177] op_sel_hi:[1,0]
	v_mul_f32_e32 v189, v189, v189
	v_mul_f32_e32 v201, v201, v201
	v_fmac_f32_e32 v179, v178, v178
	v_fmac_f32_e32 v165, v164, v164
	v_fmac_f32_e32 v197, v196, v196
	v_fmac_f32_e32 v195, v194, v194
	v_mul_f32_e32 v187, v187, v187
	v_mul_f32_e32 v199, v199, v199
	v_fmac_f32_e32 v189, v188, v188
	v_fmac_f32_e32 v201, v200, v200
	v_add_f32_e32 v164, v179, v165
	v_add_f32_e32 v165, v197, v195
	v_fmac_f32_e32 v187, v186, v186
	v_fmac_f32_e32 v199, v198, v198
	v_add_f32_e32 v164, v189, v164
	v_add_f32_e32 v165, v201, v165
	v_add_f32_e32 v164, v187, v164
	v_add_f32_e32 v165, v199, v165
	v_add_f32_e32 v178, v164, v165
	v_cndmask_b32_e64 v165, v165, v178, s[0:1]
	v_cndmask_b32_e64 v164, v164, v178, s[0:1]
	ds_bpermute_b32 v178, v184, v164
	ds_bpermute_b32 v179, v184, v165
	v_cndmask_b32_e32 v186, v202, v233, vcc
	s_waitcnt lgkmcnt(1)
	v_add_f32_e32 v164, v164, v178
	s_waitcnt lgkmcnt(0)
	v_add_f32_e32 v165, v165, v179
	ds_bpermute_b32 v179, v185, v164
	ds_bpermute_b32 v187, v185, v165
	v_mul_f32_e32 v178, v186, v176
	v_mov_b32_e32 v176, v178
	s_cbranch_scc1 .LBB0_247
	s_waitcnt lgkmcnt(0)
	v_add_f32_e32 v165, v165, v187
	v_add_f32_e32 v164, v164, v179
	v_fmaak_f32 v164, v183, v164, 0x358637bd
	v_fmaak_f32 v165, v183, v165, 0x358637bd
	v_rsq_f32_e32 v164, v164
	v_rsq_f32_e32 v165, v165
	s_nop 0
	v_pk_mul_f32 v[178:179], v[178:179], v[164:165] op_sel_hi:[0,1]
	v_mov_b32_e32 v176, v179
